# touch trimming: q~/k^T via the 32-bit saddr touch plus one load for the sibling-split v/gate rows; SC/DEC lines and the 64-bit address path dropped
# baseline (speedup 1.0000x reference)
.LBB0_250:
	v_mov_b32_e32 v4, v3
	v_mov_b32_e32 v5, v3
	v_mov_b32_e32 v100, v3
	v_mov_b32_e32 v101, v3
	v_lshl_add_u64 v[146:147], v[2:3], 1, s[56:57]
	s_lshl_b32 s22, s25, 9
	s_lshl_b32 s23, s60, 6
	v_mov_b32_e32 v2, v3
	v_mov_b32_e32 v98, v3
	v_mov_b32_e32 v99, v3
	v_mov_b64_e32 v[132:133], v[100:101]
	v_mov_b64_e32 v[104:105], v[100:101]
	v_mov_b64_e32 v[136:137], v[100:101]
	v_mov_b64_e32 v[108:109], v[100:101]
	v_mov_b64_e32 v[120:121], v[100:101]
	v_mov_b64_e32 v[112:113], v[100:101]
	v_mov_b64_e32 v[116:117], v[100:101]
	v_mov_b64_e32 v[80:81], v[4:5]
	s_add_i32 s22, s22, s0
	v_lshl_add_u32 v165, s60, 7, v207
	v_lshl_add_u32 v166, s60, 8, v206
	s_mov_b32 s74, 0
	s_lshl_b32 s23, s23, 2
	v_mov_b64_e32 v[130:131], v[98:99]
	v_mov_b64_e32 v[102:103], v[98:99]
	v_mov_b64_e32 v[134:135], v[98:99]
	v_mov_b64_e32 v[106:107], v[98:99]
	v_mov_b64_e32 v[118:119], v[98:99]
	v_mov_b64_e32 v[110:111], v[98:99]
	v_mov_b64_e32 v[114:115], v[98:99]
	v_mov_b64_e32 v[78:79], v[2:3]
	v_and_b32_e32 v240, 63, v151
	v_bfe_u32 v241, v240, 3, 2
	s_lshr_b32 s98, s92, 3
	s_and_b32 s98, s98, 15
	s_lshl_b32 s98, s98, 2
	v_add_u32_e32 v241, s98, v241
	v_mul_u32_u24_e32 v241, 0x6080, v241
	v_and_b32_e32 v242, 3, v240
	v_lshlrev_b32_e32 v242, 7, v242
	v_bfe_u32 v243, v240, 2, 1
	v_lshlrev_b32_e32 v243, 11, v243
	s_mul_i32 s99, s0, 512
	v_add3_u32 v240, v241, v242, v243
	v_add_u32_e32 v240, s99, v240
	v_and_b32_e32 v244, 63, v151
	v_mul_u32_u24_e32 v244, 0x6080, v244
	s_lshr_b32 s98, s92, 3
	s_and_b32 s98, s98, 15
	s_lshl_b32 s99, s0, 10
	s_lshl_b32 s100, s98, 6
	s_add_i32 s99, s99, s100
	s_mov_b32 s101, 16384
	s_mov_b32 s100, 4096
	s_bitcmp1_b32 s98, 0
	s_cselect_b32 s100, s101, s100
	s_add_i32 s99, s99, s100
	v_add_u32_e32 v244, s99, v244
	s_branch .LBB0_252

.LBB0_252:
	s_min_u32 s75, s74, 0x7d
	s_add_i32 s75, s75, 2
	s_lshl_b32 s26, s75, 6
	s_add_i32 s26, s26, s94
	v_mad_i64_i32 v[4:5], s[26:27], s26, v230, v[146:147]
	s_waitcnt vmcnt(8)
	v_add_co_u32_e32 v82, vcc, s81, v4
	s_waitcnt lgkmcnt(0)
	s_barrier
	s_nop 0
	v_addc_co_u32_e32 v83, vcc, 0, v5, vcc
	global_load_dwordx4 v[142:145], v[4:5], off
	global_load_dwordx4 v[138:141], v[82:83], off offset:256
	v_add_co_u32_e32 v82, vcc, s82, v4
	s_nop 1
	v_addc_co_u32_e32 v83, vcc, 0, v5, vcc
	v_add_co_u32_e32 v84, vcc, s83, v4
	s_nop 1
	v_addc_co_u32_e32 v85, vcc, 0, v5, vcc
	global_load_dwordx4 v[126:129], v[82:83], off offset:512
	global_load_dwordx4 v[122:125], v[84:85], off offset:768
	v_add_co_u32_e32 v82, vcc, s84, v4
	s_nop 1
	v_addc_co_u32_e32 v83, vcc, 0, v5, vcc
	v_add_co_u32_e32 v84, vcc, 0x3c000, v4
	s_nop 1
	v_addc_co_u32_e32 v85, vcc, 0, v5, vcc
	global_load_dwordx4 v[94:97], v[82:83], off offset:1024
	global_load_dwordx4 v[90:93], v[84:85], off offset:1280
	v_add_co_u32_e32 v82, vcc, 0x48000, v4
	s_nop 1
	v_addc_co_u32_e32 v83, vcc, 0, v5, vcc
	v_add_co_u32_e32 v4, vcc, 0x54000, v4
	s_nop 1
	v_addc_co_u32_e32 v5, vcc, 0, v5, vcc
	global_load_dwordx4 v[86:89], v[82:83], off offset:1536
	s_nop 0
	global_load_dwordx4 v[82:85], v[4:5], off offset:1792
	s_and_b64 vcc, exec, s[16:17]
	s_cbranch_vccnz .LBB0_254
	s_lshl_b32 s26, s75, 2
	s_add_i32 s26, s26, s22
	s_ashr_i32 s27, s26, 31
	s_lshl_b64 s[26:27], s[26:27], 10
	v_lshl_add_u64 v[4:5], v[158:159], 0, s[26:27]
	global_load_dwordx4 v[78:81], v[4:5], off
	s_min_u32 s99, s74, 0x7d
	s_add_i32 s99, s99, 4
	s_min_u32 s99, s99, 0x7f
	s_lshl_b32 s99, s99, 6
	s_add_i32 s99, s99, s94
	s_mul_hi_u32 s101, s99, 0x6080
	s_mul_i32 s100, s99, 0x6080
	s_add_u32 s100, s100, s56
	s_addc_u32 s101, s101, s57
	global_load_dword v241, v240, s[100:101]
	global_load_dword v241, v244, s[100:101]

.LBB0_256:
	s_min_u32 s97, s74, 0x7c
	s_add_i32 s97, s97, 3
	s_lshl_b32 s26, s97, 6
	s_add_i32 s26, s26, s94
	v_mad_i64_i32 v[18:19], s[26:27], s26, v230, v[146:147]
	v_add_co_u32_e32 v20, vcc, 0xc000, v18
	s_waitcnt lgkmcnt(0)
	s_barrier
	s_nop 0
	v_addc_co_u32_e32 v21, vcc, 0, v19, vcc
	global_load_dwordx4 v[50:53], v[18:19], off
	global_load_dwordx4 v[54:57], v[20:21], off offset:256
	v_add_co_u32_e32 v20, vcc, 0x18000, v18
	s_nop 1
	v_addc_co_u32_e32 v21, vcc, 0, v19, vcc
	v_add_co_u32_e32 v22, vcc, 0x24000, v18
	s_nop 1
	v_addc_co_u32_e32 v23, vcc, 0, v19, vcc
	global_load_dwordx4 v[38:41], v[20:21], off offset:512
	global_load_dwordx4 v[42:45], v[22:23], off offset:768
	v_add_co_u32_e32 v20, vcc, 0x30000, v18
	s_nop 1
	v_addc_co_u32_e32 v21, vcc, 0, v19, vcc
	v_add_co_u32_e32 v22, vcc, 0x3c000, v18
	s_nop 1
	v_addc_co_u32_e32 v23, vcc, 0, v19, vcc
	global_load_dwordx4 v[26:29], v[20:21], off offset:1024
	global_load_dwordx4 v[30:33], v[22:23], off offset:1280
	v_add_co_u32_e32 v20, vcc, 0x48000, v18
	s_nop 1
	v_addc_co_u32_e32 v21, vcc, 0, v19, vcc
	v_add_co_u32_e32 v22, vcc, 0x54000, v18
	s_nop 1
	v_addc_co_u32_e32 v23, vcc, 0, v19, vcc
	global_load_dwordx4 v[18:21], v[20:21], off offset:1536
	s_nop 0
	global_load_dwordx4 v[22:25], v[22:23], off offset:1792
	s_and_b64 vcc, exec, s[16:17]
	s_cbranch_vccnz .LBB0_258
	s_lshl_b32 s26, s97, 2
	s_add_i32 s26, s26, s22
	s_ashr_i32 s27, s26, 31
	s_lshl_b64 s[26:27], s[26:27], 10
	v_lshl_add_u64 v[6:7], v[158:159], 0, s[26:27]
	global_load_dwordx4 v[6:9], v[6:7], off
	s_min_u32 s99, s74, 0x7c
	s_add_i32 s99, s99, 5
	s_min_u32 s99, s99, 0x7f
	s_lshl_b32 s99, s99, 6
	s_add_i32 s99, s99, s94
	s_mul_hi_u32 s101, s99, 0x6080
	s_mul_i32 s100, s99, 0x6080
	s_add_u32 s100, s100, s56
	s_addc_u32 s101, s101, s57
	global_load_dword v241, v240, s[100:101]
	global_load_dword v241, v244, s[100:101]

.LBB0_260:
	s_cmpk_gt_u32 s74, 0x7d
	s_cbranch_scc1 .LBB0_251
	s_min_u32 s86, s74, 0x7b
	s_add_i32 s86, s86, 4
	s_lshl_b32 s26, s86, 6
	s_add_i32 s26, s26, s94
	v_mad_i64_i32 v[70:71], s[26:27], s26, v230, v[146:147]
	v_add_co_u32_e32 v14, vcc, 0xc000, v70
	s_waitcnt lgkmcnt(0)
	s_barrier
	s_nop 0
	v_addc_co_u32_e32 v15, vcc, 0, v71, vcc
	v_add_co_u32_e32 v34, vcc, 0x18000, v70
	global_load_dwordx4 v[10:13], v[70:71], off
	s_nop 0
	global_load_dwordx4 v[14:17], v[14:15], off offset:256
	v_addc_co_u32_e32 v35, vcc, 0, v71, vcc
	v_add_co_u32_e32 v46, vcc, 0x24000, v70
	s_nop 1
	v_addc_co_u32_e32 v47, vcc, 0, v71, vcc
	v_add_co_u32_e32 v62, vcc, 0x30000, v70
	global_load_dwordx4 v[34:37], v[34:35], off offset:512
	s_nop 0
	global_load_dwordx4 v[46:49], v[46:47], off offset:768
	v_addc_co_u32_e32 v63, vcc, 0, v71, vcc
	v_add_co_u32_e32 v66, vcc, 0x3c000, v70
	s_nop 1
	v_addc_co_u32_e32 v67, vcc, 0, v71, vcc
	v_add_co_u32_e32 v72, vcc, 0x48000, v70
	global_load_dwordx4 v[62:65], v[62:63], off offset:1024
	s_nop 0
	global_load_dwordx4 v[66:69], v[66:67], off offset:1280
	v_addc_co_u32_e32 v73, vcc, 0, v71, vcc
	v_add_co_u32_e32 v74, vcc, 0x54000, v70
	s_nop 1
	v_addc_co_u32_e32 v75, vcc, 0, v71, vcc
	global_load_dwordx4 v[70:73], v[72:73], off offset:1536
	s_nop 0
	global_load_dwordx4 v[74:77], v[74:75], off offset:1792
	s_and_b64 vcc, exec, s[16:17]
	s_cbranch_vccnz .LBB0_263
	s_lshl_b32 s26, s86, 2
	s_add_i32 s26, s26, s22
	s_ashr_i32 s27, s26, 31
	s_lshl_b64 s[26:27], s[26:27], 10
	v_lshl_add_u64 v[58:59], v[158:159], 0, s[26:27]
	global_load_dwordx4 v[58:61], v[58:59], off
	s_min_u32 s99, s74, 0x7b
	s_add_i32 s99, s99, 6
	s_min_u32 s99, s99, 0x7f
	s_lshl_b32 s99, s99, 6
	s_add_i32 s99, s99, s94
	s_mul_hi_u32 s101, s99, 0x6080
	s_mul_i32 s100, s99, 0x6080
	s_add_u32 s100, s100, s56
	s_addc_u32 s101, s101, s57
	global_load_dword v241, v240, s[100:101]
	global_load_dword v241, v244, s[100:101]

.LBB0_692:
	v_mov_b32_e32 v2, v1
	v_mov_b32_e32 v3, v1
	v_mov_b32_e32 v94, v1
	v_mov_b32_e32 v95, v1
	v_lshl_add_u64 v[144:145], v[0:1], 1, s[56:57]
	s_lshl_b32 s10, s13, 10
	s_lshl_b32 s11, s14, 6
	v_mov_b32_e32 v0, v1
	v_mov_b32_e32 v92, v1
	v_mov_b32_e32 v93, v1
	v_mov_b64_e32 v[130:131], v[94:95]
	v_mov_b64_e32 v[102:103], v[94:95]
	v_mov_b64_e32 v[134:135], v[94:95]
	v_mov_b64_e32 v[106:107], v[94:95]
	v_mov_b64_e32 v[118:119], v[94:95]
	v_mov_b64_e32 v[114:115], v[94:95]
	v_mov_b64_e32 v[110:111], v[94:95]
	v_mov_b64_e32 v[78:79], v[2:3]
	s_add_i32 s10, s10, s35
	v_lshl_add_u32 v149, s14, 7, v179
	v_lshl_add_u32 v150, s14, 8, v178
	s_mov_b32 s38, 0
	s_lshl_b32 s11, s11, 2
	v_mov_b64_e32 v[128:129], v[92:93]
	v_mov_b64_e32 v[100:101], v[92:93]
	v_mov_b64_e32 v[132:133], v[92:93]
	v_mov_b64_e32 v[104:105], v[92:93]
	v_mov_b64_e32 v[116:117], v[92:93]
	v_mov_b64_e32 v[112:113], v[92:93]
	v_mov_b64_e32 v[108:109], v[92:93]
	v_mov_b64_e32 v[76:77], v[0:1]
	v_and_b32_e32 v201, 63, v170
	v_bfe_u32 v202, v201, 3, 2
	s_bfe_u32 s98, s27, 0x40003
	s_and_b32 s98, s98, 15
	s_lshl_b32 s98, s98, 2
	v_add_u32_e32 v202, s98, v202
	v_mul_u32_u24_e32 v202, 0x6080, v202
	v_and_b32_e32 v203, 3, v201
	v_lshlrev_b32_e32 v203, 7, v203
	v_bfe_u32 v204, v201, 2, 1
	v_lshlrev_b32_e32 v204, 12, v204
	s_mul_i32 s99, s35, 512
	v_add3_u32 v201, v202, v203, v204
	v_add_u32_e32 v201, s99, v201
	v_and_b32_e32 v205, 63, v170
	v_mul_u32_u24_e32 v205, 0x6080, v205
	s_bfe_u32 s98, s27, 0x40003
	s_and_b32 s98, s98, 15
	s_lshl_b32 s99, s35, 10
	s_lshl_b32 s100, s98, 6
	s_add_i32 s99, s99, s100
	s_mov_b32 s101, 16384
	s_mov_b32 s100, 8192
	s_bitcmp1_b32 s98, 0
	s_cselect_b32 s100, s101, s100
	s_add_i32 s99, s99, s100
	v_add_u32_e32 v205, s99, v205
	s_branch .LBB0_694

.LBB0_694:
	s_min_u32 s39, s38, 0x7d
	s_add_i32 s39, s39, 2
	s_lshl_b32 s40, s39, 6
	s_add_i32 s40, s40, s37
	v_mad_i64_i32 v[2:3], s[40:41], s40, v194, v[144:145]
	s_waitcnt vmcnt(8)
	v_add_co_u32_e32 v80, vcc, s18, v2
	s_waitcnt lgkmcnt(0)
	s_barrier
	s_nop 0
	v_addc_co_u32_e32 v81, vcc, 0, v3, vcc
	global_load_dwordx4 v[140:143], v[2:3], off
	global_load_dwordx4 v[136:139], v[80:81], off offset:256
	v_add_co_u32_e32 v80, vcc, s19, v2
	s_nop 1
	v_addc_co_u32_e32 v81, vcc, 0, v3, vcc
	v_add_co_u32_e32 v82, vcc, s20, v2
	s_nop 1
	v_addc_co_u32_e32 v83, vcc, 0, v3, vcc
	global_load_dwordx4 v[124:127], v[80:81], off offset:512
	global_load_dwordx4 v[120:123], v[82:83], off offset:768
	v_add_co_u32_e32 v80, vcc, s21, v2
	s_nop 1
	v_addc_co_u32_e32 v81, vcc, 0, v3, vcc
	v_add_co_u32_e32 v82, vcc, 0x3c000, v2
	s_nop 1
	v_addc_co_u32_e32 v83, vcc, 0, v3, vcc
	global_load_dwordx4 v[96:99], v[80:81], off offset:1024
	global_load_dwordx4 v[88:91], v[82:83], off offset:1280
	v_add_co_u32_e32 v80, vcc, 0x48000, v2
	s_nop 1
	v_addc_co_u32_e32 v81, vcc, 0, v3, vcc
	v_add_co_u32_e32 v2, vcc, 0x54000, v2
	s_nop 1
	v_addc_co_u32_e32 v3, vcc, 0, v3, vcc
	global_load_dwordx4 v[84:87], v[80:81], off offset:1536
	s_nop 0
	global_load_dwordx4 v[80:83], v[2:3], off offset:1792
	s_and_b64 vcc, exec, s[6:7]
	s_cbranch_vccnz .LBB0_696
	s_lshl_b32 s39, s39, 3
	s_add_i32 s40, s39, s10
	s_ashr_i32 s41, s40, 31
	s_lshl_b64 s[40:41], s[40:41], 10
	v_lshl_add_u64 v[2:3], v[146:147], 0, s[40:41]
	global_load_dwordx4 v[76:79], v[2:3], off
	s_min_u32 s99, s38, 0x7d
	s_add_i32 s99, s99, 4
	s_min_u32 s99, s99, 0x7f
	s_lshl_b32 s99, s99, 6
	s_add_i32 s99, s99, s37
	s_mul_hi_u32 s101, s99, 0x6080
	s_mul_i32 s100, s99, 0x6080
	s_add_u32 s100, s100, s56
	s_addc_u32 s101, s101, s57
	global_load_dword v202, v201, s[100:101]
	global_load_dword v202, v205, s[100:101]

.LBB0_698:
	s_min_u32 s43, s38, 0x7c
	s_add_i32 s43, s43, 3
	s_lshl_b32 s44, s43, 6
	s_add_i32 s44, s44, s37
	v_mad_i64_i32 v[16:17], s[44:45], s44, v194, v[144:145]
	v_add_co_u32_e32 v18, vcc, 0xc000, v16
	s_waitcnt lgkmcnt(0)
	s_barrier
	s_nop 0
	v_addc_co_u32_e32 v19, vcc, 0, v17, vcc
	global_load_dwordx4 v[48:51], v[16:17], off
	global_load_dwordx4 v[52:55], v[18:19], off offset:256
	v_add_co_u32_e32 v18, vcc, 0x18000, v16
	s_nop 1
	v_addc_co_u32_e32 v19, vcc, 0, v17, vcc
	v_add_co_u32_e32 v20, vcc, 0x24000, v16
	s_nop 1
	v_addc_co_u32_e32 v21, vcc, 0, v17, vcc
	global_load_dwordx4 v[40:43], v[18:19], off offset:512
	global_load_dwordx4 v[44:47], v[20:21], off offset:768
	v_add_co_u32_e32 v18, vcc, 0x30000, v16
	s_nop 1
	v_addc_co_u32_e32 v19, vcc, 0, v17, vcc
	v_add_co_u32_e32 v20, vcc, 0x3c000, v16
	s_nop 1
	v_addc_co_u32_e32 v21, vcc, 0, v17, vcc
	global_load_dwordx4 v[28:31], v[18:19], off offset:1024
	global_load_dwordx4 v[32:35], v[20:21], off offset:1280
	v_add_co_u32_e32 v18, vcc, 0x48000, v16
	s_nop 1
	v_addc_co_u32_e32 v19, vcc, 0, v17, vcc
	v_add_co_u32_e32 v20, vcc, 0x54000, v16
	s_nop 1
	v_addc_co_u32_e32 v21, vcc, 0, v17, vcc
	global_load_dwordx4 v[16:19], v[18:19], off offset:1536
	s_nop 0
	global_load_dwordx4 v[20:23], v[20:21], off offset:1792
	s_and_b64 vcc, exec, s[6:7]
	s_cbranch_vccnz .LBB0_700
	s_lshl_b32 s43, s43, 3
	s_add_i32 s44, s43, s10
	s_ashr_i32 s45, s44, 31
	s_lshl_b64 s[44:45], s[44:45], 10
	v_lshl_add_u64 v[4:5], v[146:147], 0, s[44:45]
	global_load_dwordx4 v[4:7], v[4:5], off
	s_min_u32 s99, s38, 0x7c
	s_add_i32 s99, s99, 5
	s_min_u32 s99, s99, 0x7f
	s_lshl_b32 s99, s99, 6
	s_add_i32 s99, s99, s37
	s_mul_hi_u32 s101, s99, 0x6080
	s_mul_i32 s100, s99, 0x6080
	s_add_u32 s100, s100, s56
	s_addc_u32 s101, s101, s57
	global_load_dword v202, v201, s[100:101]
	global_load_dword v202, v205, s[100:101]

.LBB0_702:
	s_cmpk_gt_u32 s38, 0x7d
	s_cbranch_scc1 .LBB0_693
	s_min_u32 s40, s38, 0x7b
	s_add_i32 s40, s40, 4
	s_lshl_b32 s41, s40, 6
	s_add_i32 s41, s41, s37
	v_mad_i64_i32 v[68:69], s[42:43], s41, v194, v[144:145]
	v_add_co_u32_e32 v12, vcc, 0xc000, v68
	s_waitcnt lgkmcnt(0)
	s_barrier
	s_nop 0
	v_addc_co_u32_e32 v13, vcc, 0, v69, vcc
	v_add_co_u32_e32 v24, vcc, 0x18000, v68
	global_load_dwordx4 v[8:11], v[68:69], off
	s_nop 0
	global_load_dwordx4 v[12:15], v[12:13], off offset:256
	v_addc_co_u32_e32 v25, vcc, 0, v69, vcc
	v_add_co_u32_e32 v36, vcc, 0x24000, v68
	s_nop 1
	v_addc_co_u32_e32 v37, vcc, 0, v69, vcc
	v_add_co_u32_e32 v56, vcc, 0x30000, v68
	global_load_dwordx4 v[24:27], v[24:25], off offset:512
	s_nop 0
	global_load_dwordx4 v[36:39], v[36:37], off offset:768
	v_addc_co_u32_e32 v57, vcc, 0, v69, vcc
	v_add_co_u32_e32 v64, vcc, 0x3c000, v68
	s_nop 1
	v_addc_co_u32_e32 v65, vcc, 0, v69, vcc
	v_add_co_u32_e32 v70, vcc, 0x48000, v68
	global_load_dwordx4 v[56:59], v[56:57], off offset:1024
	s_nop 0
	global_load_dwordx4 v[64:67], v[64:65], off offset:1280
	v_addc_co_u32_e32 v71, vcc, 0, v69, vcc
	v_add_co_u32_e32 v72, vcc, 0x54000, v68
	s_nop 1
	v_addc_co_u32_e32 v73, vcc, 0, v69, vcc
	global_load_dwordx4 v[68:71], v[70:71], off offset:1536
	s_nop 0
	global_load_dwordx4 v[72:75], v[72:73], off offset:1792
	s_and_b64 vcc, exec, s[6:7]
	s_cbranch_vccnz .LBB0_705
	s_lshl_b32 s40, s40, 3
	s_add_i32 s40, s40, s10
	s_ashr_i32 s41, s40, 31
	s_lshl_b64 s[40:41], s[40:41], 10
	v_lshl_add_u64 v[60:61], v[146:147], 0, s[40:41]
	global_load_dwordx4 v[60:63], v[60:61], off
	s_min_u32 s99, s38, 0x7b
	s_add_i32 s99, s99, 6
	s_min_u32 s99, s99, 0x7f
	s_lshl_b32 s99, s99, 6
	s_add_i32 s99, s99, s37
	s_mul_hi_u32 s101, s99, 0x6080
	s_mul_i32 s100, s99, 0x6080
	s_add_u32 s100, s100, s56
	s_addc_u32 s101, s101, s57
	global_load_dword v202, v201, s[100:101]
	global_load_dword v202, v205, s[100:101]
